# combine chain: every step's C-term prefetch lands directly in that step's accumulator at step end; loop-end register rotation and its vmcnt(0) drain removed
# speedup vs baseline: 1.0014x; 1.0005x over previous
; __device__ __forceinline__ void phase_combine(const Params& p, LAS unsigned char* lds, int tid, int lane, int wave, bool dummy) {
;     ...
;             for (int seg0 = 0; seg0 < 126; seg0 += 6) {
;                 CB_STEP(seg0 + 0, 0, true); CB_STEP(seg0 + 1, 1, true); CB_STEP(seg0 + 2, 2, true);
;                 CB_STEP(seg0 + 3, 3, true); CB_STEP(seg0 + 4, 4, true); CB_STEP(seg0 + 5, 5, true);
;             }
;             CB_STEP(126, 0, false);
.LBB0_498:
	s_add_i32 s12, s12, 6
	s_min_u32 s2, s12, 0x77
	s_mulk_i32 s2, 0x6000
	s_lshl_b32 s72, s2, 2
	s_waitcnt vmcnt(15)
	ds_write_b128 v81, v[6:9] offset:16384
	ds_write_b128 v81, v[2:5] offset:16400
	v_lshl_add_u64 v[2:3], v[90:91], 0, s[72:73]
	s_mov_b64 s[6:7], 0xa8000
	v_lshl_add_u64 v[4:5], v[2:3], 0, s[6:7]
	v_add_co_u32_e32 v2, vcc, 0xa8000, v2
	v_cndmask_b32_e64 v0, 0, 1, s[8:9]
	s_nop 0
	v_addc_co_u32_e32 v3, vcc, 0, v3, vcc
	v_add_co_u32_e32 v244, vcc, 0x90000, v92
	global_load_dwordx4 v[6:9], v[2:3], off
	s_nop 0
	global_load_dwordx4 v[2:5], v[4:5], off offset:16
	v_addc_co_u32_e32 v245, vcc, 0, v93, vcc
	v_cmp_ne_u32_e64 s[6:7], 1, v0
	s_andn2_b64 vcc, exec, s[8:9]
	s_cbranch_vccnz .LBB0_500
	ds_read2st64_b32 v[200:201], v175 offset1:4
	ds_read2st64_b32 v[216:217], v176 offset0:128 offset1:129
	ds_read2st64_b32 v[202:203], v175 offset0:8 offset1:12
	ds_read2st64_b32 v[218:219], v176 offset0:130 offset1:131
	ds_read2st64_b32 v[204:205], v175 offset0:16 offset1:20
	ds_read2st64_b32 v[220:221], v176 offset0:132 offset1:133
	ds_read2st64_b32 v[206:207], v175 offset0:24 offset1:28
	ds_read2st64_b32 v[222:223], v176 offset0:134 offset1:135
	ds_read2st64_b32 v[208:209], v175 offset0:32 offset1:36
	ds_read2st64_b32 v[224:225], v176 offset0:136 offset1:137
	ds_read2st64_b32 v[210:211], v175 offset0:40 offset1:44
	ds_read2st64_b32 v[226:227], v176 offset0:138 offset1:139
	v_add_u32_e32 v0, 0x9000, v179
	s_waitcnt vmcnt(16) lgkmcnt(10)
	v_mfma_f32_16x16x4_f32 v[58:61], v200, v216, v[58:61]
	v_mfma_f32_16x16x4_f32 v[94:97], v201, v217, 0
	ds_read2st64_b32 v[212:213], v175 offset0:48 offset1:52
	ds_read2st64_b32 v[228:229], v176 offset0:140 offset1:141
	s_waitcnt lgkmcnt(10)
	v_mfma_f32_16x16x4_f32 v[58:61], v202, v218, v[58:61]
	v_mfma_f32_16x16x4_f32 v[94:97], v203, v219, v[94:97]
	ds_read2st64_b32 v[214:215], v175 offset0:56 offset1:60
	ds_read2st64_b32 v[230:231], v176 offset0:142 offset1:143
	s_waitcnt lgkmcnt(10)
	v_mfma_f32_16x16x4_f32 v[58:61], v204, v220, v[58:61]
	v_mfma_f32_16x16x4_f32 v[94:97], v205, v221, v[94:97]
	s_waitcnt lgkmcnt(8)
	v_mfma_f32_16x16x4_f32 v[58:61], v206, v222, v[58:61]
	v_mfma_f32_16x16x4_f32 v[94:97], v207, v223, v[94:97]
	s_waitcnt lgkmcnt(6)
	v_mfma_f32_16x16x4_f32 v[58:61], v208, v224, v[58:61]
	v_mfma_f32_16x16x4_f32 v[94:97], v209, v225, v[94:97]
	s_waitcnt lgkmcnt(4)
	v_mfma_f32_16x16x4_f32 v[58:61], v210, v226, v[58:61]
	v_mfma_f32_16x16x4_f32 v[94:97], v211, v227, v[94:97]
	s_waitcnt lgkmcnt(2)
	v_mfma_f32_16x16x4_f32 v[58:61], v212, v228, v[58:61]
	v_mfma_f32_16x16x4_f32 v[94:97], v213, v229, v[94:97]
	s_waitcnt lgkmcnt(0)
	v_mfma_f32_16x16x4_f32 v[58:61], v214, v230, v[58:61]
	v_mfma_f32_16x16x4_f32 v[94:97], v215, v231, v[94:97]
	s_nop 9
	v_pk_add_f32 v[60:61], v[60:61], v[96:97]
	v_pk_add_f32 v[58:59], v[58:59], v[94:95]
	global_store_dwordx4 v[92:93], v[58:61], off
	ds_write2_b32 v0, v58, v59 offset1:16
	ds_write2_b32 v0, v60, v61 offset0:32 offset1:48
.LBB0_500:
	global_load_dwordx4 v[58:61], v[244:245], off
	s_min_u32 s2, s12, 0x76
	s_mulk_i32 s2, 0x6000
	s_lshl_b32 s10, s2, 2
	s_mov_b32 s11, s73
	s_waitcnt lgkmcnt(0)
	s_barrier
	s_waitcnt vmcnt(16)
	ds_write_b128 v81, v[14:17]
	ds_write_b128 v81, v[10:13] offset:16
	v_lshl_add_u64 v[10:11], v[90:91], 0, s[10:11]
	s_mov_b64 s[16:17], 0xc0000
	v_lshl_add_u64 v[12:13], v[10:11], 0, s[16:17]
	v_add_co_u32_e32 v10, vcc, 0xc0000, v10
	v_lshl_add_u64 v[244:245], v[88:89], 0, s[72:73]
	s_nop 0
	v_addc_co_u32_e32 v11, vcc, 0, v11, vcc
	v_add_co_u32_e32 v244, vcc, 0xa8000, v244
	global_load_dwordx4 v[14:17], v[10:11], off
	s_nop 0
	global_load_dwordx4 v[10:13], v[12:13], off offset:16
	v_addc_co_u32_e32 v245, vcc, 0, v245, vcc
	s_and_b64 vcc, exec, s[6:7]
	v_add_u32_e32 v0, 0x8000, v179
	s_cbranch_vccnz .LBB0_502
	ds_read2st64_b32 v[200:201], v175 offset0:64 offset1:68
	ds_read2st64_b32 v[216:217], v176 offset0:144 offset1:145
	ds_read2st64_b32 v[202:203], v175 offset0:72 offset1:76
	ds_read2st64_b32 v[218:219], v176 offset0:146 offset1:147
	ds_read2st64_b32 v[204:205], v175 offset0:80 offset1:84
	ds_read2st64_b32 v[220:221], v176 offset0:148 offset1:149
	ds_read2st64_b32 v[206:207], v175 offset0:88 offset1:92
	ds_read2st64_b32 v[222:223], v176 offset0:150 offset1:151
	ds_read2st64_b32 v[208:209], v175 offset0:96 offset1:100
	ds_read2st64_b32 v[224:225], v176 offset0:152 offset1:153
	ds_read2st64_b32 v[210:211], v175 offset0:104 offset1:108
	ds_read2st64_b32 v[226:227], v176 offset0:154 offset1:155
	s_waitcnt vmcnt(16) lgkmcnt(10)
	v_mfma_f32_16x16x4_f32 v[66:69], v200, v216, v[66:69]
	v_mfma_f32_16x16x4_f32 v[94:97], v201, v217, 0
	ds_read2st64_b32 v[212:213], v175 offset0:112 offset1:116
	ds_read2st64_b32 v[228:229], v176 offset0:156 offset1:157
	s_waitcnt lgkmcnt(10)
	v_mfma_f32_16x16x4_f32 v[66:69], v202, v218, v[66:69]
	v_mfma_f32_16x16x4_f32 v[94:97], v203, v219, v[94:97]
	ds_read2st64_b32 v[214:215], v175 offset0:120 offset1:124
	ds_read2st64_b32 v[230:231], v176 offset0:158 offset1:159
	s_waitcnt lgkmcnt(10)
	v_mfma_f32_16x16x4_f32 v[66:69], v204, v220, v[66:69]
	v_mfma_f32_16x16x4_f32 v[94:97], v205, v221, v[94:97]
	s_waitcnt lgkmcnt(8)
	v_mfma_f32_16x16x4_f32 v[66:69], v206, v222, v[66:69]
	v_mfma_f32_16x16x4_f32 v[94:97], v207, v223, v[94:97]
	s_waitcnt lgkmcnt(6)
	v_mfma_f32_16x16x4_f32 v[66:69], v208, v224, v[66:69]
	v_mfma_f32_16x16x4_f32 v[94:97], v209, v225, v[94:97]
	s_waitcnt lgkmcnt(4)
	v_mfma_f32_16x16x4_f32 v[66:69], v210, v226, v[66:69]
	v_mfma_f32_16x16x4_f32 v[94:97], v211, v227, v[94:97]
	s_waitcnt lgkmcnt(2)
	v_mfma_f32_16x16x4_f32 v[66:69], v212, v228, v[66:69]
	v_mfma_f32_16x16x4_f32 v[94:97], v213, v229, v[94:97]
	s_waitcnt lgkmcnt(0)
	v_mfma_f32_16x16x4_f32 v[66:69], v214, v230, v[66:69]
	v_mfma_f32_16x16x4_f32 v[94:97], v215, v231, v[94:97]
	s_nop 9
	v_pk_add_f32 v[66:67], v[66:67], v[94:95]
	v_add_co_u32_e32 v94, vcc, 0x18000, v92
	v_pk_add_f32 v[68:69], v[68:69], v[96:97]
	s_nop 0
	v_addc_co_u32_e32 v95, vcc, 0, v93, vcc
	global_store_dwordx4 v[94:95], v[66:69], off
	ds_write2_b32 v0, v66, v67 offset1:16
	ds_write2_b32 v0, v68, v69 offset0:32 offset1:48
; __device__ __forceinline__ void phase_combine(const Params& p, LAS unsigned char* lds, int tid, int lane, int wave, bool dummy) {
;     ...
;             for (int seg0 = 0; seg0 < 126; seg0 += 6) {
;                 CB_STEP(seg0 + 0, 0, true); CB_STEP(seg0 + 1, 1, true); CB_STEP(seg0 + 2, 2, true);
;                 CB_STEP(seg0 + 3, 3, true); CB_STEP(seg0 + 4, 4, true); CB_STEP(seg0 + 5, 5, true);
;             }
;             CB_STEP(126, 0, false);
.LBB0_502:
	global_load_dwordx4 v[66:69], v[244:245], off
	s_min_u32 s2, s12, 0x75
	s_mulk_i32 s2, 0x6000
	s_lshl_b32 s72, s2, 2
	s_waitcnt lgkmcnt(0)
	s_barrier
	s_waitcnt vmcnt(17)
	ds_write_b128 v81, v[18:21] offset:16384
	s_waitcnt vmcnt(16)
	ds_write_b128 v81, v[22:25] offset:16400
	v_lshl_add_u64 v[18:19], v[90:91], 0, s[72:73]
	s_mov_b64 s[16:17], 0xd8000
	v_lshl_add_u64 v[22:23], v[18:19], 0, s[16:17]
	v_add_co_u32_e32 v18, vcc, 0xd8000, v18
	v_lshl_add_u64 v[244:245], v[88:89], 0, s[10:11]
	s_nop 0
	v_addc_co_u32_e32 v19, vcc, 0, v19, vcc
	v_add_co_u32_e32 v244, vcc, 0xc0000, v244
	global_load_dwordx4 v[18:21], v[18:19], off
	s_nop 0
	global_load_dwordx4 v[22:25], v[22:23], off offset:16
	v_addc_co_u32_e32 v245, vcc, 0, v245, vcc
	s_and_b64 vcc, exec, s[6:7]
	s_cbranch_vccnz .LBB0_504
	ds_read2st64_b32 v[200:201], v175 offset1:4
	ds_read2st64_b32 v[216:217], v176 offset0:128 offset1:129
	ds_read2st64_b32 v[202:203], v175 offset0:8 offset1:12
	ds_read2st64_b32 v[218:219], v176 offset0:130 offset1:131
	ds_read2st64_b32 v[204:205], v175 offset0:16 offset1:20
	ds_read2st64_b32 v[220:221], v176 offset0:132 offset1:133
	ds_read2st64_b32 v[206:207], v175 offset0:24 offset1:28
	ds_read2st64_b32 v[222:223], v176 offset0:134 offset1:135
	ds_read2st64_b32 v[208:209], v175 offset0:32 offset1:36
	ds_read2st64_b32 v[224:225], v176 offset0:136 offset1:137
	ds_read2st64_b32 v[210:211], v175 offset0:40 offset1:44
	ds_read2st64_b32 v[226:227], v176 offset0:138 offset1:139
	s_waitcnt vmcnt(16) lgkmcnt(10)
	v_mfma_f32_16x16x4_f32 v[74:77], v200, v216, v[74:77]
	v_mfma_f32_16x16x4_f32 v[94:97], v201, v217, 0
	ds_read2st64_b32 v[212:213], v175 offset0:48 offset1:52
	ds_read2st64_b32 v[228:229], v176 offset0:140 offset1:141
	s_waitcnt lgkmcnt(10)
	v_mfma_f32_16x16x4_f32 v[74:77], v202, v218, v[74:77]
	v_mfma_f32_16x16x4_f32 v[94:97], v203, v219, v[94:97]
	ds_read2st64_b32 v[214:215], v175 offset0:56 offset1:60
	ds_read2st64_b32 v[230:231], v176 offset0:142 offset1:143
	s_waitcnt lgkmcnt(10)
	v_mfma_f32_16x16x4_f32 v[74:77], v204, v220, v[74:77]
	v_mfma_f32_16x16x4_f32 v[94:97], v205, v221, v[94:97]
	s_waitcnt lgkmcnt(8)
	v_mfma_f32_16x16x4_f32 v[74:77], v206, v222, v[74:77]
	v_mfma_f32_16x16x4_f32 v[94:97], v207, v223, v[94:97]
	s_waitcnt lgkmcnt(6)
	v_mfma_f32_16x16x4_f32 v[74:77], v208, v224, v[74:77]
	v_mfma_f32_16x16x4_f32 v[94:97], v209, v225, v[94:97]
	s_waitcnt lgkmcnt(4)
	v_mfma_f32_16x16x4_f32 v[74:77], v210, v226, v[74:77]
	v_mfma_f32_16x16x4_f32 v[94:97], v211, v227, v[94:97]
	s_waitcnt lgkmcnt(2)
	v_mfma_f32_16x16x4_f32 v[74:77], v212, v228, v[74:77]
	v_mfma_f32_16x16x4_f32 v[94:97], v213, v229, v[94:97]
	s_waitcnt lgkmcnt(0)
	v_mfma_f32_16x16x4_f32 v[74:77], v214, v230, v[74:77]
	v_mfma_f32_16x16x4_f32 v[94:97], v215, v231, v[94:97]
	s_nop 9
	v_pk_add_f32 v[74:75], v[74:75], v[94:95]
	v_add_co_u32_e32 v94, vcc, 0x30000, v92
	v_pk_add_f32 v[76:77], v[76:77], v[96:97]
	s_nop 0
	v_addc_co_u32_e32 v95, vcc, 0, v93, vcc
	global_store_dwordx4 v[94:95], v[74:77], off
	v_add_u32_e32 v94, 0x9000, v179
	ds_write2_b32 v94, v74, v75 offset1:16
	ds_write2_b32 v94, v76, v77 offset0:32 offset1:48
.LBB0_504:
	global_load_dwordx4 v[74:77], v[244:245], off
	s_min_u32 s2, s12, 0x74
	s_mulk_i32 s2, 0x6000
	s_lshl_b32 s10, s2, 2
	s_mov_b32 s11, s73
	s_waitcnt lgkmcnt(0)
	s_barrier
	s_waitcnt vmcnt(16)
	ds_write_b128 v81, v[30:33]
	ds_write_b128 v81, v[26:29] offset:16
	v_lshl_add_u64 v[26:27], v[90:91], 0, s[10:11]
	s_mov_b64 s[16:17], 0xf0000
	v_lshl_add_u64 v[28:29], v[26:27], 0, s[16:17]
	v_add_co_u32_e32 v26, vcc, 0xf0000, v26
	v_lshl_add_u64 v[244:245], v[88:89], 0, s[72:73]
	s_nop 0
	v_addc_co_u32_e32 v27, vcc, 0, v27, vcc
	v_add_co_u32_e32 v244, vcc, 0xd8000, v244
	global_load_dwordx4 v[30:33], v[26:27], off
	s_nop 0
	global_load_dwordx4 v[26:29], v[28:29], off offset:16
	v_addc_co_u32_e32 v245, vcc, 0, v245, vcc
	s_and_b64 vcc, exec, s[6:7]
	s_cbranch_vccnz .LBB0_506
	ds_read2st64_b32 v[200:201], v175 offset0:64 offset1:68
	ds_read2st64_b32 v[216:217], v176 offset0:144 offset1:145
	ds_read2st64_b32 v[202:203], v175 offset0:72 offset1:76
	ds_read2st64_b32 v[218:219], v176 offset0:146 offset1:147
	ds_read2st64_b32 v[204:205], v175 offset0:80 offset1:84
	ds_read2st64_b32 v[220:221], v176 offset0:148 offset1:149
	ds_read2st64_b32 v[206:207], v175 offset0:88 offset1:92
	ds_read2st64_b32 v[222:223], v176 offset0:150 offset1:151
	ds_read2st64_b32 v[208:209], v175 offset0:96 offset1:100
	ds_read2st64_b32 v[224:225], v176 offset0:152 offset1:153
	ds_read2st64_b32 v[210:211], v175 offset0:104 offset1:108
	ds_read2st64_b32 v[226:227], v176 offset0:154 offset1:155
	s_waitcnt vmcnt(16) lgkmcnt(10)
	v_mfma_f32_16x16x4_f32 v[70:73], v200, v216, v[70:73]
	v_mfma_f32_16x16x4_f32 v[94:97], v201, v217, 0
	ds_read2st64_b32 v[212:213], v175 offset0:112 offset1:116
	ds_read2st64_b32 v[228:229], v176 offset0:156 offset1:157
	s_waitcnt lgkmcnt(10)
	v_mfma_f32_16x16x4_f32 v[70:73], v202, v218, v[70:73]
	v_mfma_f32_16x16x4_f32 v[94:97], v203, v219, v[94:97]
	ds_read2st64_b32 v[214:215], v175 offset0:120 offset1:124
	ds_read2st64_b32 v[230:231], v176 offset0:158 offset1:159
	s_waitcnt lgkmcnt(10)
	v_mfma_f32_16x16x4_f32 v[70:73], v204, v220, v[70:73]
	v_mfma_f32_16x16x4_f32 v[94:97], v205, v221, v[94:97]
	s_waitcnt lgkmcnt(8)
	v_mfma_f32_16x16x4_f32 v[70:73], v206, v222, v[70:73]
	v_mfma_f32_16x16x4_f32 v[94:97], v207, v223, v[94:97]
	s_waitcnt lgkmcnt(6)
	v_mfma_f32_16x16x4_f32 v[70:73], v208, v224, v[70:73]
	v_mfma_f32_16x16x4_f32 v[94:97], v209, v225, v[94:97]
	s_waitcnt lgkmcnt(4)
	v_mfma_f32_16x16x4_f32 v[70:73], v210, v226, v[70:73]
	v_mfma_f32_16x16x4_f32 v[94:97], v211, v227, v[94:97]
	s_waitcnt lgkmcnt(2)
	v_mfma_f32_16x16x4_f32 v[70:73], v212, v228, v[70:73]
	v_mfma_f32_16x16x4_f32 v[94:97], v213, v229, v[94:97]
	s_waitcnt lgkmcnt(0)
	v_mfma_f32_16x16x4_f32 v[70:73], v214, v230, v[70:73]
	v_mfma_f32_16x16x4_f32 v[94:97], v215, v231, v[94:97]
	s_nop 9
	v_pk_add_f32 v[70:71], v[70:71], v[94:95]
	v_add_co_u32_e32 v94, vcc, 0x48000, v92
	v_pk_add_f32 v[72:73], v[72:73], v[96:97]
	s_nop 0
	v_addc_co_u32_e32 v95, vcc, 0, v93, vcc
	global_store_dwordx4 v[94:95], v[70:73], off
	ds_write2_b32 v0, v70, v71 offset1:16
	ds_write2_b32 v0, v72, v73 offset0:32 offset1:48
; __device__ __forceinline__ void phase_combine(const Params& p, LAS unsigned char* lds, int tid, int lane, int wave, bool dummy) {
;     ...
;             for (int seg0 = 0; seg0 < 126; seg0 += 6) {
;                 CB_STEP(seg0 + 0, 0, true); CB_STEP(seg0 + 1, 1, true); CB_STEP(seg0 + 2, 2, true);
;                 CB_STEP(seg0 + 3, 3, true); CB_STEP(seg0 + 4, 4, true); CB_STEP(seg0 + 5, 5, true);
;             }
;             CB_STEP(126, 0, false);
.LBB0_506:
	global_load_dwordx4 v[70:73], v[244:245], off
	s_min_u32 s2, s12, 0x73
	s_mulk_i32 s2, 0x6000
	s_lshl_b32 s72, s2, 2
	s_waitcnt lgkmcnt(0)
	s_barrier
	s_waitcnt vmcnt(17)
	ds_write_b128 v81, v[34:37] offset:16384
	s_waitcnt vmcnt(16)
	ds_write_b128 v81, v[38:41] offset:16400
	v_lshl_add_u64 v[34:35], v[90:91], 0, s[72:73]
	s_mov_b64 s[16:17], 0x108000
	v_lshl_add_u64 v[38:39], v[34:35], 0, s[16:17]
	v_add_co_u32_e32 v34, vcc, 0x108000, v34
	v_lshl_add_u64 v[244:245], v[88:89], 0, s[10:11]
	s_nop 0
	v_addc_co_u32_e32 v35, vcc, 0, v35, vcc
	v_add_co_u32_e32 v244, vcc, 0xf0000, v244
	global_load_dwordx4 v[34:37], v[34:35], off
	s_nop 0
	global_load_dwordx4 v[38:41], v[38:39], off offset:16
	v_addc_co_u32_e32 v245, vcc, 0, v245, vcc
	s_and_b64 vcc, exec, s[6:7]
	s_cbranch_vccnz .LBB0_508
	ds_read2st64_b32 v[200:201], v175 offset1:4
	ds_read2st64_b32 v[216:217], v176 offset0:128 offset1:129
	ds_read2st64_b32 v[202:203], v175 offset0:8 offset1:12
	ds_read2st64_b32 v[218:219], v176 offset0:130 offset1:131
	ds_read2st64_b32 v[204:205], v175 offset0:16 offset1:20
	ds_read2st64_b32 v[220:221], v176 offset0:132 offset1:133
	ds_read2st64_b32 v[206:207], v175 offset0:24 offset1:28
	ds_read2st64_b32 v[222:223], v176 offset0:134 offset1:135
	ds_read2st64_b32 v[208:209], v175 offset0:32 offset1:36
	ds_read2st64_b32 v[224:225], v176 offset0:136 offset1:137
	ds_read2st64_b32 v[210:211], v175 offset0:40 offset1:44
	ds_read2st64_b32 v[226:227], v176 offset0:138 offset1:139
	s_waitcnt vmcnt(16) lgkmcnt(10)
	v_mfma_f32_16x16x4_f32 v[62:65], v200, v216, v[62:65]
	v_mfma_f32_16x16x4_f32 v[94:97], v201, v217, 0
	ds_read2st64_b32 v[212:213], v175 offset0:48 offset1:52
	ds_read2st64_b32 v[228:229], v176 offset0:140 offset1:141
	s_waitcnt lgkmcnt(10)
	v_mfma_f32_16x16x4_f32 v[62:65], v202, v218, v[62:65]
	v_mfma_f32_16x16x4_f32 v[94:97], v203, v219, v[94:97]
	ds_read2st64_b32 v[214:215], v175 offset0:56 offset1:60
	ds_read2st64_b32 v[230:231], v176 offset0:142 offset1:143
	s_waitcnt lgkmcnt(10)
	v_mfma_f32_16x16x4_f32 v[62:65], v204, v220, v[62:65]
	v_mfma_f32_16x16x4_f32 v[94:97], v205, v221, v[94:97]
	s_waitcnt lgkmcnt(8)
	v_mfma_f32_16x16x4_f32 v[62:65], v206, v222, v[62:65]
	v_mfma_f32_16x16x4_f32 v[94:97], v207, v223, v[94:97]
	s_waitcnt lgkmcnt(6)
	v_mfma_f32_16x16x4_f32 v[62:65], v208, v224, v[62:65]
	v_mfma_f32_16x16x4_f32 v[94:97], v209, v225, v[94:97]
	s_waitcnt lgkmcnt(4)
	v_mfma_f32_16x16x4_f32 v[62:65], v210, v226, v[62:65]
	v_mfma_f32_16x16x4_f32 v[94:97], v211, v227, v[94:97]
	s_waitcnt lgkmcnt(2)
	v_mfma_f32_16x16x4_f32 v[62:65], v212, v228, v[62:65]
	v_mfma_f32_16x16x4_f32 v[94:97], v213, v229, v[94:97]
	s_waitcnt lgkmcnt(0)
	v_mfma_f32_16x16x4_f32 v[62:65], v214, v230, v[62:65]
	v_mfma_f32_16x16x4_f32 v[94:97], v215, v231, v[94:97]
	s_nop 9
	v_pk_add_f32 v[62:63], v[62:63], v[94:95]
	v_add_co_u32_e32 v94, vcc, 0x60000, v92
	v_pk_add_f32 v[64:65], v[64:65], v[96:97]
	s_nop 0
	v_addc_co_u32_e32 v95, vcc, 0, v93, vcc
	global_store_dwordx4 v[94:95], v[62:65], off
	v_add_u32_e32 v94, 0x9000, v179
	ds_write2_b32 v94, v62, v63 offset1:16
	ds_write2_b32 v94, v64, v65 offset0:32 offset1:48
; __device__ __forceinline__ void phase_combine(const Params& p, LAS unsigned char* lds, int tid, int lane, int wave, bool dummy) {
;     ...
;             for (int seg0 = 0; seg0 < 126; seg0 += 6) {
;                 CB_STEP(seg0 + 0, 0, true); CB_STEP(seg0 + 1, 1, true); CB_STEP(seg0 + 2, 2, true);
;                 CB_STEP(seg0 + 3, 3, true); CB_STEP(seg0 + 4, 4, true); CB_STEP(seg0 + 5, 5, true);
;             }
;             CB_STEP(126, 0, false);
.LBB0_508:
	global_load_dwordx4 v[62:65], v[244:245], off
	s_min_u32 s2, s12, 0x72
	s_mul_i32 s10, s2, 0x18000
	s_mov_b32 s11, s73
	s_waitcnt lgkmcnt(0)
	s_barrier
	s_waitcnt vmcnt(16)
	ds_write_b128 v81, v[46:49]
	ds_write_b128 v81, v[42:45] offset:16
	v_lshl_add_u64 v[42:43], v[90:91], 0, s[10:11]
	s_mov_b64 s[10:11], 0x120000
	v_lshl_add_u64 v[44:45], v[42:43], 0, s[10:11]
	v_add_co_u32_e32 v42, vcc, 0x120000, v42
	v_lshl_add_u64 v[244:245], v[88:89], 0, s[72:73]
	s_nop 0
	v_addc_co_u32_e32 v43, vcc, 0, v43, vcc
	v_add_co_u32_e32 v244, vcc, 0x108000, v244
	global_load_dwordx4 v[46:49], v[42:43], off
	s_nop 0
	global_load_dwordx4 v[42:45], v[44:45], off offset:16
	v_addc_co_u32_e32 v245, vcc, 0, v245, vcc
	s_and_b64 vcc, exec, s[6:7]
	s_cbranch_vccnz .LBB0_510
	ds_read2st64_b32 v[200:201], v175 offset0:64 offset1:68
	ds_read2st64_b32 v[216:217], v176 offset0:144 offset1:145
	ds_read2st64_b32 v[202:203], v175 offset0:72 offset1:76
	ds_read2st64_b32 v[218:219], v176 offset0:146 offset1:147
	ds_read2st64_b32 v[204:205], v175 offset0:80 offset1:84
	ds_read2st64_b32 v[220:221], v176 offset0:148 offset1:149
	ds_read2st64_b32 v[206:207], v175 offset0:88 offset1:92
	ds_read2st64_b32 v[222:223], v176 offset0:150 offset1:151
	ds_read2st64_b32 v[208:209], v175 offset0:96 offset1:100
	ds_read2st64_b32 v[224:225], v176 offset0:152 offset1:153
	ds_read2st64_b32 v[210:211], v175 offset0:104 offset1:108
	ds_read2st64_b32 v[226:227], v176 offset0:154 offset1:155
	s_waitcnt vmcnt(16) lgkmcnt(10)
	v_mfma_f32_16x16x4_f32 v[54:57], v200, v216, v[54:57]
	v_mfma_f32_16x16x4_f32 v[94:97], v201, v217, 0
	ds_read2st64_b32 v[212:213], v175 offset0:112 offset1:116
	ds_read2st64_b32 v[228:229], v176 offset0:156 offset1:157
	s_waitcnt lgkmcnt(10)
	v_mfma_f32_16x16x4_f32 v[54:57], v202, v218, v[54:57]
	v_mfma_f32_16x16x4_f32 v[94:97], v203, v219, v[94:97]
	ds_read2st64_b32 v[214:215], v175 offset0:120 offset1:124
	ds_read2st64_b32 v[230:231], v176 offset0:158 offset1:159
	s_waitcnt lgkmcnt(10)
	v_mfma_f32_16x16x4_f32 v[54:57], v204, v220, v[54:57]
	v_mfma_f32_16x16x4_f32 v[94:97], v205, v221, v[94:97]
	s_waitcnt lgkmcnt(8)
	v_mfma_f32_16x16x4_f32 v[54:57], v206, v222, v[54:57]
	v_mfma_f32_16x16x4_f32 v[94:97], v207, v223, v[94:97]
	s_waitcnt lgkmcnt(6)
	v_mfma_f32_16x16x4_f32 v[54:57], v208, v224, v[54:57]
	v_mfma_f32_16x16x4_f32 v[94:97], v209, v225, v[94:97]
	s_waitcnt lgkmcnt(4)
	v_mfma_f32_16x16x4_f32 v[54:57], v210, v226, v[54:57]
	v_mfma_f32_16x16x4_f32 v[94:97], v211, v227, v[94:97]
	s_waitcnt lgkmcnt(2)
	v_mfma_f32_16x16x4_f32 v[54:57], v212, v228, v[54:57]
	v_mfma_f32_16x16x4_f32 v[94:97], v213, v229, v[94:97]
	s_waitcnt lgkmcnt(0)
	v_mfma_f32_16x16x4_f32 v[54:57], v214, v230, v[54:57]
	v_mfma_f32_16x16x4_f32 v[94:97], v215, v231, v[94:97]
	s_nop 9
	v_pk_add_f32 v[54:55], v[54:55], v[94:95]
	v_add_co_u32_e32 v94, vcc, 0x78000, v92
	v_pk_add_f32 v[56:57], v[56:57], v[96:97]
	s_nop 0
	v_addc_co_u32_e32 v95, vcc, 0, v93, vcc
	global_store_dwordx4 v[94:95], v[54:57], off
	ds_write2_b32 v0, v54, v55 offset1:16
	ds_write2_b32 v0, v56, v57 offset0:32 offset1:48
.LBB0_510:
	global_load_dwordx4 v[54:57], v[244:245], off
	s_waitcnt lgkmcnt(0)
	s_barrier
	v_lshl_add_u64 v[92:93], v[92:93], 0, s[88:89]
	s_cmpk_gt_u32 s12, 0x77
	s_cbranch_scc1 .LBB0_512
	s_branch .LBB0_498
.LBB0_512:
	s_and_b64 vcc, exec, s[8:9]
	s_waitcnt vmcnt(17)
	ds_write_b128 v81, v[6:9] offset:16384
	s_waitcnt vmcnt(16)
	ds_write_b128 v81, v[2:5] offset:16400
	s_cbranch_vccz .LBB0_481
	ds_read2st64_b32 v[200:201], v177 offset1:4
	ds_read2st64_b32 v[216:217], v178 offset0:128 offset1:129
	ds_read2st64_b32 v[202:203], v177 offset0:8 offset1:12
	ds_read2st64_b32 v[218:219], v178 offset0:130 offset1:131
	ds_read2st64_b32 v[204:205], v177 offset0:16 offset1:20
	ds_read2st64_b32 v[220:221], v178 offset0:132 offset1:133
	ds_read2st64_b32 v[206:207], v177 offset0:24 offset1:28
	ds_read2st64_b32 v[222:223], v178 offset0:134 offset1:135
	ds_read2st64_b32 v[208:209], v177 offset0:32 offset1:36
	ds_read2st64_b32 v[224:225], v178 offset0:136 offset1:137
	ds_read2st64_b32 v[210:211], v177 offset0:40 offset1:44
	ds_read2st64_b32 v[226:227], v178 offset0:138 offset1:139
	v_add_u32_e32 v0, 0x9000, v179
	s_waitcnt vmcnt(13) lgkmcnt(10)
	v_mfma_f32_16x16x4_f32 v[2:5], v200, v216, v[58:61]
	v_mfma_f32_16x16x4_f32 v[6:9], v201, v217, 0
	ds_read2st64_b32 v[212:213], v177 offset0:48 offset1:52
	ds_read2st64_b32 v[228:229], v178 offset0:140 offset1:141
	s_waitcnt lgkmcnt(10)
	v_mfma_f32_16x16x4_f32 v[2:5], v202, v218, v[2:5]
	v_mfma_f32_16x16x4_f32 v[6:9], v203, v219, v[6:9]
	ds_read2st64_b32 v[214:215], v177 offset0:56 offset1:60
	ds_read2st64_b32 v[230:231], v178 offset0:142 offset1:143
	s_waitcnt lgkmcnt(10)
	v_mfma_f32_16x16x4_f32 v[2:5], v204, v220, v[2:5]
	v_mfma_f32_16x16x4_f32 v[6:9], v205, v221, v[6:9]
	s_waitcnt lgkmcnt(8)
	v_mfma_f32_16x16x4_f32 v[2:5], v206, v222, v[2:5]
	v_mfma_f32_16x16x4_f32 v[6:9], v207, v223, v[6:9]
	s_waitcnt lgkmcnt(6)
	v_mfma_f32_16x16x4_f32 v[2:5], v208, v224, v[2:5]
	v_mfma_f32_16x16x4_f32 v[6:9], v209, v225, v[6:9]
	s_waitcnt lgkmcnt(4)
	v_mfma_f32_16x16x4_f32 v[2:5], v210, v226, v[2:5]
	v_mfma_f32_16x16x4_f32 v[6:9], v211, v227, v[6:9]
	s_waitcnt lgkmcnt(2)
	v_mfma_f32_16x16x4_f32 v[2:5], v212, v228, v[2:5]
	v_mfma_f32_16x16x4_f32 v[6:9], v213, v229, v[6:9]
	s_waitcnt lgkmcnt(0)
	v_mfma_f32_16x16x4_f32 v[2:5], v214, v230, v[2:5]
	v_mfma_f32_16x16x4_f32 v[6:9], v215, v231, v[6:9]
	s_nop 9
	v_pk_add_f32 v[2:3], v[2:3], v[6:7]
	v_add_co_u32_e32 v6, vcc, 0xbd0000, v88
	v_pk_add_f32 v[4:5], v[4:5], v[8:9]
	s_nop 0
	v_addc_co_u32_e32 v7, vcc, 0, v89, vcc
	global_store_dwordx4 v[6:7], v[2:5], off
	ds_write2_b32 v0, v2, v3 offset1:16
	ds_write2_b32 v0, v4, v5 offset0:32 offset1:48
	s_branch .LBB0_481
